# norm f32-path drains removed; sync-only grid barrier (no L2 write-back) at 4 write-after-read seams
# speedup vs baseline: 1.0196x; 1.0026x over previous
; __device__ __forceinline__ void norm_phase(int upd_l, int upd_s, int h_l, int h_s, int xsrc, int xdst, bool dummy, int vc) {
;     ...
;             if (row + 3 * rstep < rend) NP_LOAD(row + 3 * rstep, v3, xb3, yb3);
.LBB0_337:
	v_lshlrev_b64 v[68:69], 12, v[196:197]
	v_lshl_add_u64 v[80:81], v[92:93], 0, v[68:69]
	global_load_dwordx4 v[68:71], v[80:81], off
	global_load_dwordx4 v[72:75], v[80:81], off offset:1024
	global_load_dwordx4 v[76:79], v[80:81], off offset:2048
	s_nop 0
	global_load_dwordx4 v[80:83], v[80:81], off offset:3072
	s_and_b64 vcc, exec, s[42:43]
	s_cbranch_vccz .LBB0_277
	s_branch .LBB0_278

; __device__ __forceinline__ void norm_phase(int upd_l, int upd_s, int h_l, int h_s, int xsrc, int xdst, bool dummy, int vc) {
;     ...
;             if (row + 4 * rstep < rend) NP_LOAD(row + 4 * rstep, v0, xb0, yb0);
.LBB0_339:
	v_lshlrev_b64 v[36:37], 12, v[208:209]
	v_lshl_add_u64 v[48:49], v[92:93], 0, v[36:37]
	global_load_dwordx4 v[36:39], v[48:49], off
	global_load_dwordx4 v[40:43], v[48:49], off offset:1024
	global_load_dwordx4 v[44:47], v[48:49], off offset:2048
	s_nop 0
	global_load_dwordx4 v[48:51], v[48:49], off offset:3072
	s_and_b64 vcc, exec, s[42:43]
	s_cbranch_vccz .LBB0_292
	s_branch .LBB0_293

; __device__ __forceinline__ void norm_phase(int upd_l, int upd_s, int h_l, int h_s, int xsrc, int xdst, bool dummy, int vc) {
;     ...
;             if (row + 5 * rstep < rend) NP_LOAD(row + 5 * rstep, v1, xb1, yb1);
.LBB0_341:
	v_lshlrev_b64 v[4:5], 12, v[208:209]
	v_lshl_add_u64 v[16:17], v[92:93], 0, v[4:5]
	global_load_dwordx4 v[4:7], v[16:17], off
	global_load_dwordx4 v[8:11], v[16:17], off offset:1024
	global_load_dwordx4 v[12:15], v[16:17], off offset:2048
	s_nop 0
	global_load_dwordx4 v[16:19], v[16:17], off offset:3072
	s_and_b64 vcc, exec, s[42:43]
	s_cbranch_vccz .LBB0_308
	s_branch .LBB0_309

; __device__ __forceinline__ void norm_phase(int upd_l, int upd_s, int h_l, int h_s, int xsrc, int xdst, bool dummy, int vc) {
;     ...
;             if (row + 6 * rstep < rend) NP_LOAD(row + 6 * rstep, v2, xb2, yb2);
.LBB0_343:
	v_lshlrev_b64 v[52:53], 12, v[206:207]
	v_lshl_add_u64 v[64:65], v[92:93], 0, v[52:53]
	global_load_dwordx4 v[52:55], v[64:65], off
	global_load_dwordx4 v[56:59], v[64:65], off offset:1024
	global_load_dwordx4 v[60:63], v[64:65], off offset:2048
	s_nop 0
	global_load_dwordx4 v[64:67], v[64:65], off offset:3072
	s_and_b64 vcc, exec, s[42:43]
	s_cbranch_vccz .LBB0_324
	s_branch .LBB0_325

; __device__ __forceinline__ unsigned xb_ld(unsigned* p)              { return __hip_atomic_load(p, __ATOMIC_RELAXED, __HIP_MEMORY_SCOPE_AGENT); }
; __device__ __forceinline__ unsigned xb_add(unsigned* p, unsigned v) { return __hip_atomic_fetch_add(p, v, __ATOMIC_RELAXED, __HIP_MEMORY_SCOPE_AGENT); }
; #define XB_SPIN(cond, bar) do { unsigned _sp = 0; while (cond) { __builtin_amdgcn_s_sleep(1); \
;     if ((++_sp & 255u) == 0u) { if (xb_ld(&(bar)[XB_TMO])) break; if (_sp > XB_SPIN_CAP) { atomicAdd(&(bar)[XB_TMO], 1u); break; } } } } while (0)
; __device__ __forceinline__ void xcd_barrier(const XcdBarrier& b) {
;     ...
;         const unsigned old = xb_add(&bar[XB_XSUB(b.x)], 1u);
;         const unsigned gen = old / nloc;
;         if (old + 1u == (gen + 1u) * nloc) {
;             __builtin_amdgcn_fence(__ATOMIC_RELEASE, "agent");
;             asm volatile("s_waitcnt vmcnt(0)" ::: "memory");
;             const unsigned og = xb_add(&bar[XB_TOP], 1u);
;             const unsigned tg = og / nx;
;             if (og + 1u == (tg + 1u) * nx) xb_add(&bar[XB_TOPGEN], 1u);
;             else XB_SPIN(xb_ld(&bar[XB_TOPGEN]) == tg, bar);
.LBB0_800:
	v_readlane_b32 s8, v254, 52
	s_add_u32 s8, s2, s8
	s_addc_u32 s9, s3, 0
	v_cvt_f32_u32_e32 v0, v3
	v_sub_u32_e32 v5, 0, v3
	v_rcp_iflag_f32_e32 v0, v0
	global_atomic_add v4, v219, v223, s[8:9] offset:1024 sc0
	s_add_u32 s8, s8, 0x13a40000
	s_addc_u32 s9, s9, 0
	v_mul_f32_e32 v0, 0x4f7ffffe, v0
	v_cvt_u32_f32_e32 v0, v0
	v_mul_lo_u32 v5, v5, v0
	v_mul_hi_u32 v5, v0, v5
	v_add_u32_e32 v0, v0, v5
	s_waitcnt vmcnt(0)
	v_mul_hi_u32 v0, v4, v0
	v_mul_lo_u32 v5, v0, v3
	v_sub_u32_e32 v5, v4, v5
	v_add_u32_e32 v6, 1, v0
	v_cmp_ge_u32_e32 vcc, v5, v3
	v_add_u32_e32 v4, 1, v4
	s_nop 0
	v_cndmask_b32_e32 v0, v0, v6, vcc
	v_sub_u32_e32 v6, v5, v3
	v_cndmask_b32_e32 v5, v5, v6, vcc
	v_add_u32_e32 v6, 1, v0
	v_cmp_ge_u32_e32 vcc, v5, v3
	s_nop 1
	v_cndmask_b32_e32 v0, v0, v6, vcc
	v_mul_lo_u32 v5, v3, v0
	v_add_u32_e32 v3, v5, v3
	v_cmp_ne_u32_e32 vcc, v4, v3
	s_and_saveexec_b64 s[10:11], vcc
	s_xor_b64 s[10:11], exec, s[10:11]
	s_cbranch_execz .LBB0_814
	v_readlane_b32 s20, v255, 59
	s_mov_b32 s21, 0x36650e
	s_lshr_b32 s21, s21, s26
	s_and_b32 s20, s20, s21
	s_bitcmp1_b32 s20, 0
	s_cbranch_scc1 .Lbar_local_early
	v_add_u32_e32 v6, 1, v5
	v_cmp_eq_u32_e32 vcc, v4, v6
	s_cbranch_vccz .Lbar_early_done
	v_readlane_b32 s20, v255, 59
	s_mov_b32 s21, 0x4008a0
	s_lshr_b32 s21, s21, s26
	s_and_b32 s20, s20, s21
	s_bitcmp1_b32 s20, 0
	s_cbranch_scc1 .Lbar_early_done
	buffer_wbl2 sc1
	s_branch .Lbar_early_done

; __device__ __forceinline__ unsigned xb_add(unsigned* p, unsigned v) { return __hip_atomic_fetch_add(p, v, __ATOMIC_RELAXED, __HIP_MEMORY_SCOPE_AGENT); }
; __device__ __forceinline__ void xcd_barrier(const XcdBarrier& b) {
;     ...
;         if (old + 1u == (gen + 1u) * nloc) {
;             __builtin_amdgcn_fence(__ATOMIC_RELEASE, "agent");
;             asm volatile("s_waitcnt vmcnt(0)" ::: "memory");
;             const unsigned og = xb_add(&bar[XB_TOP], 1u);
;             const unsigned tg = og / nx;
;             if (og + 1u == (tg + 1u) * nx) xb_add(&bar[XB_TOPGEN], 1u);
.Lbar_noinv:
.LBB0_814:
	s_andn2_saveexec_b64 s[10:11], s[10:11]
	s_cbranch_execz .LBB0_832
	s_mov_b64 s[10:11], exec
	v_readlane_b32 s18, v255, 59
	s_mov_b32 s19, 0x36650e
	s_lshr_b32 s19, s19, s26
	s_and_b32 s18, s18, s19
	s_bitcmp1_b32 s18, 0
	s_cbranch_scc1 .LBB0_831
	v_readlane_b32 s18, v255, 59
	s_mov_b32 s19, 0x4008a0
	s_lshr_b32 s19, s19, s26
	s_and_b32 s18, s18, s19
	s_bitcmp1_b32 s18, 0
	s_cbranch_scc1 .Lbar_nowb
	buffer_wbl2 sc1
.Lbar_nowb:
	s_waitcnt lgkmcnt(0)
	s_waitcnt vmcnt(0)
	v_mbcnt_lo_u32_b32 v0, s10, 0
	v_mbcnt_hi_u32_b32 v0, s11, v0
	v_cmp_eq_u32_e32 vcc, 0, v0
	s_and_saveexec_b64 s[18:19], vcc
	s_cbranch_execz .LBB0_817
	s_bcnt1_i32_b64 s10, s[10:11]
	v_mov_b32_e32 v3, s10
	v_mov_b32_e32 v4, 0x13a43000
	global_atomic_add v3, v4, v3, s[2:3] offset:1024 sc0
